# attention phase B: three priority levels (compute core 2, next-stage address/loads 1, tile staging waits and writes 0)
# baseline (speedup 1.0000x reference)
.LBB0_529:
	s_setprio 0
	s_add_i32 s1, s65, s41
	s_lshl_b32 s0, s65, 4
	s_lshl_b32 s1, s1, 8
	s_add_i32 s10, s0, s42
	s_and_b32 s14, s1, 0x700
	s_ashr_i32 s0, s10, 3
	s_or_b32 s8, s14, s43
	s_ashr_i32 s1, s0, 31
	s_add_i32 s18, s8, s44
	s_lshl_b64 s[0:1], s[0:1], 11
	s_ashr_i32 s11, s18, 31
	s_add_u32 s12, s0, s18
	s_addc_u32 s11, s1, s11
	s_or_b32 s10, s10, s40
	v_mov_b32_e32 v3, s11
	s_ashr_i32 s11, s10, 31
	v_or_b32_e32 v2, s12, v174
	s_lshl_b64 s[12:13], s[10:11], 18
	s_add_u32 s10, s48, s12
	s_addc_u32 s11, s49, s13
	s_add_u32 s12, s50, s12
	s_waitcnt vmcnt(12)
	v_add_u32_e32 v43, s14, v188
	v_lshlrev_b64 v[2:3], 10, v[2:3]
	s_addc_u32 s13, s51, s13
	v_med3_i32 v0, v43, 0, v210
	v_lshl_add_u64 v[2:3], v[178:179], 0, v[2:3]
	s_waitcnt vmcnt(7)
	v_lshl_add_u64 v[44:45], s[10:11], 0, v[184:185]
	v_lshl_add_u64 v[48:49], s[12:13], 0, v[184:185]
	v_lshlrev_b32_e32 v0, 7, v0
	global_load_dwordx4 v[136:139], v[2:3], off nt
	global_load_dwordx4 v[132:135], v[2:3], off offset:64 nt
	v_lshl_add_u64 v[2:3], v[44:45], 0, v[0:1]
	v_lshl_add_u64 v[6:7], v[48:49], 0, v[0:1]
	v_max_i32_e32 v0, 0xffffffc0, v43
	v_add_u32_e32 v0, 64, v0
	v_min_u32_e32 v0, 0x7ff, v0
	v_lshlrev_b32_e32 v0, 7, v0
	v_lshl_add_u64 v[10:11], v[44:45], 0, v[0:1]
	v_lshl_add_u64 v[14:15], v[48:49], 0, v[0:1]
	v_add_u32_e32 v0, s14, v181
	v_med3_i32 v0, v0, 0, v210
	v_lshlrev_b32_e32 v0, 7, v0
	v_lshl_add_u64 v[18:19], v[44:45], 0, v[0:1]
	v_lshl_add_u64 v[22:23], v[48:49], 0, v[0:1]
	v_max_i32_e32 v0, 0xffffff40, v43
	v_add_u32_e32 v0, 0xc0, v0
	v_min_u32_e32 v0, 0x7ff, v0
	v_lshlrev_b32_e32 v0, 7, v0
	v_lshl_add_u64 v[26:27], v[44:45], 0, v[0:1]
	v_lshl_add_u64 v[30:31], v[48:49], 0, v[0:1]
	v_max_i32_e32 v0, 0xffffff00, v43
	v_add_u32_e32 v0, 0x100, v0
	v_min_u32_e32 v0, 0x7ff, v0
	v_lshlrev_b32_e32 v0, 7, v0
	v_lshl_add_u64 v[34:35], v[44:45], 0, v[0:1]
	v_lshl_add_u64 v[38:39], v[48:49], 0, v[0:1]
	v_max_i32_e32 v0, 0xfffffec0, v43
	v_add_u32_e32 v0, 0x140, v0
	v_min_u32_e32 v0, 0x7ff, v0
	v_lshlrev_b32_e32 v0, 7, v0
	v_lshl_add_u64 v[46:47], v[44:45], 0, v[0:1]
	v_lshl_add_u64 v[54:55], v[48:49], 0, v[0:1]
	global_load_dwordx4 v[2:5], v[2:3], off
	s_nop 0
	global_load_dwordx4 v[6:9], v[6:7], off
	s_nop 0
	global_load_dwordx4 v[10:13], v[10:11], off
	s_nop 0
	global_load_dwordx4 v[14:17], v[14:15], off
	s_nop 0
	global_load_dwordx4 v[18:21], v[18:19], off
	s_nop 0
	global_load_dwordx4 v[22:25], v[22:23], off
	s_nop 0
	global_load_dwordx4 v[26:29], v[26:27], off
	s_nop 0
	global_load_dwordx4 v[30:33], v[30:31], off
	s_nop 0
	global_load_dwordx4 v[34:37], v[34:35], off
	s_nop 0
	global_load_dwordx4 v[38:41], v[38:39], off
	s_nop 0
	global_load_dwordx4 v[50:53], v[46:47], off
	s_nop 0
	global_load_dwordx4 v[54:57], v[54:55], off
	s_and_saveexec_b64 s[14:15], s[4:5]
	s_cbranch_execz .LBB0_531
	v_max_i32_e32 v0, 0xfffffe80, v43
	v_add_u32_e32 v0, 0x180, v0
	v_min_u32_e32 v0, 0x7ff, v0
	v_lshlrev_b32_e32 v0, 7, v0
	v_lshl_add_u64 v[46:47], v[48:49], 0, v[0:1]
	v_lshl_add_u64 v[42:43], v[44:45], 0, v[0:1]
	global_load_dwordx4 v[42:45], v[42:43], off
	s_nop 0
	global_load_dwordx4 v[46:49], v[46:47], off

.LBB0_546:
	s_cmp_eq_u32 s77, 1
	s_cselect_b32 s0, 2, 4
	s_lshr_b32 s1, 16, s0
	s_lshl_b32 s18, s67, 6
	s_setprio 0
	s_waitcnt vmcnt(14) lgkmcnt(2)
	ds_write_b128 v219, v[12:15]
	s_waitcnt vmcnt(12)
	ds_write_b128 v219, v[24:27] offset:1152
	s_waitcnt vmcnt(10)
	ds_write_b128 v219, v[32:35] offset:2304
	s_waitcnt vmcnt(8)
	ds_write_b128 v219, v[40:43] offset:3456
	s_waitcnt vmcnt(6)
	ds_write_b128 v219, v[52:55] offset:4608
	s_waitcnt vmcnt(4)
	ds_write_b128 v219, v[64:67] offset:5760
	s_waitcnt vmcnt(2)
	ds_write_b128 v219, v[76:79] offset:6912
	s_waitcnt vmcnt(0)
	ds_write_b128 v219, v[88:91] offset:8064
	s_waitcnt lgkmcnt(8)
	ds_write_b128 v220, v[4:7] offset:9216
	ds_write_b128 v220, v[8:11] offset:10240
	ds_write_b128 v220, v[16:19] offset:11264
	ds_write_b128 v220, v[20:23] offset:12288
	ds_write_b128 v220, v[28:31] offset:13312
	ds_write_b128 v220, v[36:39] offset:14336
	ds_write_b128 v220, v[44:47] offset:15360
	ds_write_b128 v220, v[68:71] offset:16384
	s_setprio 2
	v_mul_u32_u24_e32 v2, s1, v173
	s_sub_i32 s16, 0x80, s18
	s_lshr_b32 s0, s8, s0
	v_mov_b32_e32 v3, s16
	s_sub_i32 s19, s16, s0
	v_subrev_u32_e32 v2, s18, v2
	v_add_u32_e32 v228, v207, v192
	v_add_u32_e32 v230, v207, v194
	v_mad_u32_u24 v18, s1, v173, v3
	s_cmp_lg_u32 s77, 2
	v_max_i32_e32 v19, s19, v2
	v_add_u32_e32 v229, v207, v193
	ds_read_b128 v[10:13], v228 offset:9216
	ds_read_b128 v[14:17], v229 offset:9216
	v_add_u32_e32 v231, v207, v195
	ds_read_b128 v[6:9], v230 offset:9728
	ds_read_b128 v[2:5], v231 offset:9728
	s_cselect_b64 s[0:1], -1, 0
	s_cmp_lg_u32 s67, 2
	s_cselect_b64 s[16:17], -1, 0
	s_or_b64 s[0:1], s[16:17], s[0:1]
	v_sub_u32_e32 v18, v18, v19
	v_sub_u32_e32 v25, v176, v19
	s_mov_b64 s[16:17], -1
	s_and_b64 vcc, exec, s[0:1]
	v_add_u32_e32 v225, s45, v175
	v_cmp_le_u32_e64 s[0:1], v25, v18
	v_add_u32_e32 v26, 1, v25
	v_add_u32_e32 v24, 2, v25
	v_add_u32_e32 v23, 3, v25
	v_add_u32_e32 v22, 4, v25
	v_add_u32_e32 v21, 5, v25
	v_add_u32_e32 v20, 6, v25
	v_add_u32_e32 v19, 7, v25
	s_cbranch_vccz .LBB0_548
	s_waitcnt vmcnt(1) lgkmcnt(3)
	v_mfma_f32_16x16x32_bf16 v[28:31], v[10:13], v[132:135], 0
	ds_read_b128 v[32:35], v228 offset:13312
	ds_read_b128 v[36:39], v229 offset:13312
	v_cmp_le_u32_e32 vcc, v26, v18
	ds_read_b128 v[40:43], v230 offset:13824
	ds_read_b128 v[44:47], v231 offset:13824
	s_waitcnt vmcnt(0) lgkmcnt(6)
	v_mfma_f32_16x16x32_bf16 v[28:31], v[14:17], v[136:139], v[28:31]
	s_mov_b64 s[16:17], 0
	s_waitcnt lgkmcnt(5)
	v_mfma_f32_16x16x32_bf16 v[52:55], v[6:9], v[132:135], 0
	s_waitcnt lgkmcnt(4)
	v_mfma_f32_16x16x32_bf16 v[52:55], v[2:5], v[136:139], v[52:55]
	s_nop 2
	v_cndmask_b32_e32 v64, v217, v29, vcc
	v_cmp_le_u32_e32 vcc, v24, v18
	v_cndmask_b32_e64 v27, v217, v28, s[0:1]
	s_nop 0
	v_cndmask_b32_e32 v65, v217, v30, vcc
	v_cmp_le_u32_e32 vcc, v23, v18
	s_nop 1
	v_cndmask_b32_e32 v66, v217, v31, vcc
	s_waitcnt lgkmcnt(3)
	v_mfma_f32_16x16x32_bf16 v[28:31], v[32:35], v[132:135], 0
	v_cmp_le_u32_e32 vcc, v22, v18
	s_nop 1
	v_cndmask_b32_e32 v52, v217, v52, vcc
	v_cmp_le_u32_e32 vcc, v21, v18
	s_waitcnt lgkmcnt(2)
	v_mfma_f32_16x16x32_bf16 v[28:31], v[36:39], v[136:139], v[28:31]
	v_add_u32_e32 v37, 32, v25
	v_cndmask_b32_e32 v53, v217, v53, vcc
	v_cmp_le_u32_e32 vcc, v20, v18
	s_waitcnt lgkmcnt(1)
	v_mfma_f32_16x16x32_bf16 v[32:35], v[40:43], v[132:135], 0
	v_cndmask_b32_e32 v54, v217, v54, vcc
	v_cmp_le_u32_e32 vcc, v19, v18
	s_waitcnt lgkmcnt(0)
	v_mfma_f32_16x16x32_bf16 v[32:35], v[44:47], v[136:139], v[32:35]
	v_cndmask_b32_e32 v36, v217, v55, vcc
	v_cmp_le_u32_e32 vcc, v37, v18
	v_add_u32_e32 v37, 33, v25
	s_nop 0
	v_cndmask_b32_e32 v28, v217, v28, vcc
	v_cmp_le_u32_e32 vcc, v37, v18
	v_add_u32_e32 v37, 34, v25
	s_nop 0
	v_cndmask_b32_e32 v29, v217, v29, vcc
	v_cmp_le_u32_e32 vcc, v37, v18
	v_add_u32_e32 v37, 35, v25
	s_nop 0
	v_cndmask_b32_e32 v30, v217, v30, vcc
	v_cmp_le_u32_e32 vcc, v37, v18
	v_add_u32_e32 v37, 36, v25
	s_nop 0
	v_cndmask_b32_e32 v31, v217, v31, vcc
	v_cmp_le_u32_e32 vcc, v37, v18
	v_add_u32_e32 v37, 37, v25
	s_nop 0
	v_cndmask_b32_e32 v32, v217, v32, vcc
	v_cmp_le_u32_e32 vcc, v37, v18
	v_add_u32_e32 v37, 38, v25
	s_nop 0
	v_cndmask_b32_e32 v33, v217, v33, vcc
	v_cmp_le_u32_e32 vcc, v37, v18
	v_add_u32_e32 v37, 39, v25
	s_nop 0
	v_cndmask_b32_e32 v34, v217, v34, vcc
	v_cmp_le_u32_e32 vcc, v37, v18
	v_max3_f32 v37, v27, s62, v64
	v_max3_f32 v37, v37, v65, v66
	v_max3_f32 v37, v37, v52, v53
	v_max3_f32 v37, v37, v54, v36
	v_max3_f32 v37, v37, v28, v29
	v_max3_f32 v37, v37, v30, v31
	v_cndmask_b32_e32 v35, v217, v35, vcc
	v_max3_f32 v37, v37, v32, v33
	v_max3_f32 v37, v37, v34, v35
	ds_bpermute_b32 v38, v0, v37
	s_waitcnt lgkmcnt(0)
	v_max_f32_e32 v38, v38, v38
	v_max_f32_e32 v37, v37, v38
	ds_bpermute_b32 v38, v222, v37
	s_waitcnt lgkmcnt(0)
	v_max3_f32 v226, v223, v37, v38
	v_sub_f32_e32 v27, v27, v226
	v_exp_f32_e32 v27, v27
	v_sub_f32_e32 v38, v64, v226
	v_exp_f32_e32 v38, v38
	v_sub_f32_e32 v39, v65, v226
	v_sub_f32_e32 v28, v28, v226
	v_exp_f32_e32 v39, v39
	v_sub_f32_e32 v40, v66, v226
	v_exp_f32_e32 v90, v28
	v_sub_f32_e32 v28, v29, v226
	v_exp_f32_e32 v40, v40
	v_sub_f32_e32 v42, v52, v226
	v_exp_f32_e32 v91, v28
	v_sub_f32_e32 v28, v30, v226
	v_add_f32_e32 v41, 0, v27
	v_exp_f32_e32 v42, v42
	v_sub_f32_e32 v43, v53, v226
	v_exp_f32_e32 v156, v28
	v_sub_f32_e32 v28, v31, v226
	v_add_f32_e32 v41, v38, v41
	v_exp_f32_e32 v43, v43
	v_sub_f32_e32 v44, v54, v226
	v_exp_f32_e32 v160, v28
	v_sub_f32_e32 v28, v32, v226
	v_add_f32_e32 v41, v39, v41
	v_exp_f32_e32 v44, v44
	v_sub_f32_e32 v36, v36, v226
	v_exp_f32_e32 v161, v28
	v_sub_f32_e32 v28, v33, v226
	v_sub_f32_e32 v37, v223, v226
	v_add_f32_e32 v41, v40, v41
	v_exp_f32_e32 v36, v36
	v_exp_f32_e32 v162, v28
	v_sub_f32_e32 v28, v34, v226
	v_add_f32_e32 v41, v42, v41
	v_exp_f32_e32 v164, v28
	v_sub_f32_e32 v64, v35, v226
	v_exp_f32_e32 v88, v37
	v_cvt_pk_bf16_f32 v28, v27, v38
	v_cvt_pk_bf16_f32 v29, v39, v40
	v_cvt_pk_bf16_f32 v30, v42, v43
	v_cvt_pk_bf16_f32 v31, v44, v36
	ds_read_b64_tr_b16 v[34:35], v225 offset:576
	ds_read_b64_tr_b16 v[32:33], v225
	v_add_f32_e32 v41, v43, v41
	v_add_f32_e32 v41, v44, v41
	v_add_f32_e32 v89, v36, v41
	ds_read_b64_tr_b16 v[42:43], v225 offset:608
	ds_read_b64_tr_b16 v[40:41], v225 offset:32
	ds_read_b64_tr_b16 v[44:45], v225 offset:64
	ds_read_b64_tr_b16 v[52:53], v225 offset:96
	ds_read_b64_tr_b16 v[46:47], v225 offset:640
	ds_read_b64_tr_b16 v[54:55], v225 offset:672
	v_pk_mul_f32 v[38:39], v[154:155], v[88:89] op_sel_hi:[1,0]
	v_pk_mul_f32 v[36:37], v[152:153], v[88:89] op_sel_hi:[1,0]
	v_exp_f32_e32 v27, v64
	v_pk_mul_f32 v[66:67], v[142:143], v[88:89] op_sel_hi:[1,0]
	s_waitcnt lgkmcnt(6)
	v_mfma_f32_16x16x32_bf16 v[32:35], v[32:35], v[28:31], v[36:39]
	v_mul_f32_e64 v64, v140, v88
	v_mul_f32_e64 v65, v141, v88
	s_nop 0
	v_pk_mul_f32 v[38:39], v[150:151], v[88:89] op_sel_hi:[1,0]
	v_pk_mul_f32 v[36:37], v[148:149], v[88:89] op_sel_hi:[1,0]
	s_waitcnt lgkmcnt(4)
	s_nop 0
	v_mfma_f32_16x16x32_bf16 v[36:39], v[40:43], v[28:31], v[36:39]
	v_mul_f32_e64 v42, v146, v88
	v_mul_f32_e64 v43, v147, v88
	v_pk_mul_f32 v[40:41], v[144:145], v[88:89] op_sel_hi:[1,0]
	s_waitcnt lgkmcnt(1)
	s_nop 0
	v_mfma_f32_16x16x32_bf16 v[40:43], v[44:47], v[28:31], v[40:43]
	v_cvt_pk_bf16_f32 v44, v90, v91
	v_cvt_pk_bf16_f32 v45, v156, v160
	v_cvt_pk_bf16_f32 v46, v161, v162
	v_cvt_pk_bf16_f32 v47, v164, v27
	ds_read_b64_tr_b16 v[70:71], v225 offset:5184
	ds_read_b64_tr_b16 v[68:69], v225 offset:4608
	s_waitcnt lgkmcnt(0)
	v_mfma_f32_16x16x32_bf16 v[168:171], v[68:71], v[44:47], v[32:35]
	s_nop 2
	v_add_f32_e32 v32, v90, v89
	v_add_f32_e32 v32, v91, v32
	v_add_f32_e32 v32, v156, v32
	v_mfma_f32_16x16x32_bf16 v[28:31], v[52:55], v[28:31], v[64:67]
	ds_read_b64_tr_b16 v[54:55], v225 offset:5216
	ds_read_b64_tr_b16 v[52:53], v225 offset:4640
	s_nop 0
	ds_read_b64_tr_b16 v[64:65], v225 offset:4672
	ds_read_b64_tr_b16 v[76:77], v225 offset:4704
	ds_read_b64_tr_b16 v[66:67], v225 offset:5248
	ds_read_b64_tr_b16 v[78:79], v225 offset:5280
	v_add_f32_e32 v32, v160, v32
	v_add_f32_e32 v32, v161, v32
	v_add_f32_e32 v32, v162, v32
	s_waitcnt lgkmcnt(0)
	v_add_f32_e32 v32, v164, v32
	v_add_f32_e32 v227, v27, v32
	s_waitcnt lgkmcnt(4)
	v_mfma_f32_16x16x32_bf16 v[156:159], v[52:55], v[44:47], v[36:39]
	v_fmac_f32_e32 v227, v224, v88
	s_waitcnt lgkmcnt(1)
	v_mfma_f32_16x16x32_bf16 v[160:163], v[64:67], v[44:47], v[40:43]
	s_waitcnt lgkmcnt(0)
	v_mfma_f32_16x16x32_bf16 v[164:167], v[76:79], v[44:47], v[28:31]

.LBB0_550:
	s_setprio 1
	s_cmp_lt_i32 s67, 2
	s_cselect_b64 s[18:19], -1, 0
	s_cmp_lt_i32 s77, 2
	s_cselect_b64 s[38:39], -1, 0
	s_or_b64 s[16:17], s[18:19], s[38:39]
	s_mov_b64 s[0:1], -1
	v_readfirstlane_b32 s81, v0
	v_readfirstlane_b32 s82, v0
	v_readfirstlane_b32 s79, v0
	s_andn2_b64 vcc, exec, s[16:17]
	v_readfirstlane_b32 s80, v0
	s_cbranch_vccnz .LBB0_544
	s_cmp_eq_u32 s75, 1
	s_cselect_b32 s0, 2, 4
	s_lshr_b32 s16, s8, s0
	s_lshl_b32 s17, s76, 6
	s_lshr_b32 s1, 0x800, s0
	s_add_i32 s16, s16, s17
	s_add_i32 s1, s1, -1
	v_add_u32_e32 v68, s16, v191
	s_waitcnt lgkmcnt(0)
	v_min_i32_e32 v2, s1, v68
	v_cmp_lt_i32_e32 vcc, -1, v68
	s_lshl_b32 s20, -1, s0
	s_andn2_b32 s20, s8, s20
	v_cndmask_b32_e32 v2, 0, v2, vcc
	v_lshlrev_b32_e32 v2, s0, v2
	v_add_u32_e32 v2, s20, v2
	v_lshl_or_b32 v2, v2, 6, v180
	v_ashrrev_i32_e32 v3, 31, v2
	v_lshlrev_b64 v[2:3], 1, v[2:3]
	v_lshl_add_u64 v[4:5], s[10:11], 0, v[2:3]
	v_lshl_add_u64 v[2:3], s[12:13], 0, v[2:3]
	global_load_dwordx4 v[4:7], v[4:5], off
	s_nop 0
	global_load_dwordx4 v[12:15], v[2:3], off
	v_add_u32_e32 v2, 8, v68
	v_min_i32_e32 v3, s1, v2
	v_cmp_lt_i32_e32 vcc, -1, v2
	s_mov_b64 s[16:17], 0
	s_nop 0
	v_cndmask_b32_e32 v2, 0, v3, vcc
	v_lshlrev_b32_e32 v2, s0, v2
	v_add_u32_e32 v2, s20, v2
	v_lshl_or_b32 v2, v2, 6, v180
	v_ashrrev_i32_e32 v3, 31, v2
	v_lshlrev_b64 v[2:3], 1, v[2:3]
	v_lshl_add_u64 v[8:9], s[10:11], 0, v[2:3]
	v_lshl_add_u64 v[2:3], s[12:13], 0, v[2:3]
	global_load_dwordx4 v[8:11], v[8:9], off
	s_nop 0
	global_load_dwordx4 v[24:27], v[2:3], off
	v_add_u32_e32 v2, 16, v68
	v_min_i32_e32 v3, s1, v2
	v_cmp_lt_i32_e32 vcc, -1, v2
	s_nop 1
	v_cndmask_b32_e32 v2, 0, v3, vcc
	v_lshlrev_b32_e32 v2, s0, v2
	v_add_u32_e32 v2, s20, v2
	v_lshl_or_b32 v2, v2, 6, v180
	v_ashrrev_i32_e32 v3, 31, v2
	v_lshlrev_b64 v[2:3], 1, v[2:3]
	v_lshl_add_u64 v[16:17], s[10:11], 0, v[2:3]
	v_lshl_add_u64 v[2:3], s[12:13], 0, v[2:3]
	global_load_dwordx4 v[16:19], v[16:17], off
	s_nop 0
	global_load_dwordx4 v[32:35], v[2:3], off
	v_add_u32_e32 v2, 24, v68
	v_min_i32_e32 v3, s1, v2
	v_cmp_lt_i32_e32 vcc, -1, v2
	s_nop 1
	v_cndmask_b32_e32 v2, 0, v3, vcc
	v_lshlrev_b32_e32 v2, s0, v2
	v_add_u32_e32 v2, s20, v2
	v_lshl_or_b32 v2, v2, 6, v180
	v_ashrrev_i32_e32 v3, 31, v2
	v_lshlrev_b64 v[2:3], 1, v[2:3]
	v_lshl_add_u64 v[20:21], s[10:11], 0, v[2:3]
	v_lshl_add_u64 v[2:3], s[12:13], 0, v[2:3]
	global_load_dwordx4 v[20:23], v[20:21], off
	s_nop 0
	global_load_dwordx4 v[40:43], v[2:3], off
	v_add_u32_e32 v2, 32, v68
	v_min_i32_e32 v3, s1, v2
	v_cmp_lt_i32_e32 vcc, -1, v2
	s_nop 1
	v_cndmask_b32_e32 v2, 0, v3, vcc
	v_lshlrev_b32_e32 v2, s0, v2
	v_add_u32_e32 v2, s20, v2
	v_lshl_or_b32 v2, v2, 6, v180
	v_ashrrev_i32_e32 v3, 31, v2
	v_lshlrev_b64 v[2:3], 1, v[2:3]
	v_lshl_add_u64 v[28:29], s[10:11], 0, v[2:3]
	v_lshl_add_u64 v[2:3], s[12:13], 0, v[2:3]
	global_load_dwordx4 v[28:31], v[28:29], off
	s_nop 0
	global_load_dwordx4 v[52:55], v[2:3], off
	v_add_u32_e32 v2, 40, v68
	v_min_i32_e32 v3, s1, v2
	v_cmp_lt_i32_e32 vcc, -1, v2
	s_nop 1
	v_cndmask_b32_e32 v2, 0, v3, vcc
	v_lshlrev_b32_e32 v2, s0, v2
	v_add_u32_e32 v2, s20, v2
	v_lshl_or_b32 v2, v2, 6, v180
	v_ashrrev_i32_e32 v3, 31, v2
	v_lshlrev_b64 v[2:3], 1, v[2:3]
	v_lshl_add_u64 v[36:37], s[10:11], 0, v[2:3]
	v_lshl_add_u64 v[2:3], s[12:13], 0, v[2:3]
	global_load_dwordx4 v[36:39], v[36:37], off
	s_nop 0
	global_load_dwordx4 v[64:67], v[2:3], off
	v_add_u32_e32 v2, 48, v68
	v_min_i32_e32 v3, s1, v2
	v_cmp_lt_i32_e32 vcc, -1, v2
	s_nop 1
	v_cndmask_b32_e32 v2, 0, v3, vcc
	v_lshlrev_b32_e32 v2, s0, v2
	v_add_u32_e32 v2, s20, v2
	v_lshl_or_b32 v2, v2, 6, v180
	v_ashrrev_i32_e32 v3, 31, v2
	v_lshlrev_b64 v[2:3], 1, v[2:3]
	v_lshl_add_u64 v[44:45], s[10:11], 0, v[2:3]
	v_lshl_add_u64 v[2:3], s[12:13], 0, v[2:3]
	global_load_dwordx4 v[44:47], v[44:45], off
	s_nop 0
	global_load_dwordx4 v[76:79], v[2:3], off
	v_add_u32_e32 v2, 56, v68
	v_min_i32_e32 v3, s1, v2
	v_cmp_lt_i32_e32 vcc, -1, v2
	s_nop 1
	v_cndmask_b32_e32 v2, 0, v3, vcc
	v_lshlrev_b32_e32 v2, s0, v2
	v_add_u32_e32 v2, s20, v2
	v_lshl_or_b32 v2, v2, 6, v180
	v_ashrrev_i32_e32 v3, 31, v2
	v_lshlrev_b64 v[2:3], 1, v[2:3]
	v_lshl_add_u64 v[68:69], s[10:11], 0, v[2:3]
	v_lshl_add_u64 v[2:3], s[12:13], 0, v[2:3]
	global_load_dwordx4 v[68:71], v[68:69], off
	s_nop 0
	global_load_dwordx4 v[88:91], v[2:3], off
	s_andn2_b64 vcc, exec, s[14:15]
	s_cbranch_vccnz .LBB0_555
	s_add_i32 s0, s76, 1
	s_cmp_lt_i32 s76, 2
	s_mov_b64 s[16:17], -1
	s_cbranch_scc1 .LBB0_554
	s_add_i32 s1, s75, 1
	s_cmp_lt_i32 s75, 2
	s_cselect_b64 s[16:17], -1, 0
	s_and_b64 s[14:15], s[16:17], exec
	s_cselect_b32 s0, s66, s0
	s_mov_b32 s75, s1

.LBB0_555:
	s_add_i32 s67, s67, 1
	s_and_b64 s[0:1], s[38:39], exec
	s_cselect_b32 s14, s66, s67
	s_and_b64 s[0:1], s[18:19], exec
	s_cselect_b32 s78, s67, s14
	s_xor_b64 s[0:1], s[18:19], -1
	v_cndmask_b32_e64 v2, 0, 1, s[0:1]
	s_setprio 0
	s_waitcnt vmcnt(32)
	ds_write_b128 v219, v[48:51]
	s_waitcnt vmcnt(30)
	ds_write_b128 v219, v[60:63] offset:1152
	s_waitcnt vmcnt(28)
	ds_write_b128 v219, v[80:83] offset:2304
	s_waitcnt vmcnt(26)
	ds_write_b128 v219, v[92:95] offset:3456
	s_waitcnt vmcnt(24)
	ds_write_b128 v219, v[100:103] offset:4608
	s_waitcnt vmcnt(22)
	ds_write_b128 v219, v[108:111] offset:5760
	s_waitcnt vmcnt(20)
	ds_write_b128 v219, v[116:119] offset:6912
	s_waitcnt vmcnt(18)
	ds_write_b128 v219, v[124:127] offset:8064
	ds_write_b128 v220, v[56:59] offset:9216
	ds_write_b128 v220, v[72:75] offset:10240
	ds_write_b128 v220, v[84:87] offset:11264
	ds_write_b128 v220, v[96:99] offset:12288
	ds_write_b128 v220, v[104:107] offset:13312
	ds_write_b128 v220, v[112:115] offset:14336
	ds_write_b128 v220, v[120:123] offset:15360
	s_setprio 2
	ds_write_b128 v220, v[128:131] offset:16384
	v_readfirstlane_b32 s0, v2
	s_add_i32 s67, s77, s0
	s_cmp_eq_u32 s67, 1
	s_cselect_b32 s0, 2, 4
	s_lshl_b32 s20, s78, 6
	s_lshr_b32 s1, 16, s0
	s_sub_i32 s18, 0x80, s20
	s_lshr_b32 s0, s8, s0
	ds_read_b128 v[60:63], v228 offset:9216
	ds_read_b128 v[72:75], v229 offset:9216
	ds_read_b128 v[56:59], v230 offset:9728
	ds_read_b128 v[48:51], v231 offset:9728
	s_sub_i32 s21, s18, s0
	v_mul_u32_u24_e32 v2, s1, v173
	v_mov_b32_e32 v3, s18
	s_cmp_lg_u32 s67, 2
	v_mad_u32_u24 v3, s1, v173, v3
	s_cselect_b64 s[0:1], -1, 0
	s_cmp_lg_u32 s78, 2
	v_subrev_u32_e32 v2, s20, v2
	s_cselect_b64 s[18:19], -1, 0
	v_max_i32_e32 v80, s21, v2
	s_or_b64 s[0:1], s[0:1], s[18:19]
	v_sub_u32_e32 v2, v3, v80
	v_sub_u32_e32 v85, v176, v80
	s_mov_b64 s[14:15], -1
	s_and_b64 vcc, exec, s[0:1]
	v_cmp_le_u32_e64 s[0:1], v85, v2
	v_add_u32_e32 v86, 1, v85
	v_add_u32_e32 v84, 2, v85
	v_add_u32_e32 v83, 3, v85
	v_add_u32_e32 v82, 4, v85
	v_add_u32_e32 v81, 5, v85
	v_add_u32_e32 v80, 6, v85
	v_add_u32_e32 v3, 7, v85
	s_cbranch_vccz .LBB0_557
	s_waitcnt vmcnt(17) lgkmcnt(3)
	v_mfma_f32_16x16x32_bf16 v[92:95], v[60:63], v[132:135], 0
	ds_read_b128 v[96:99], v228 offset:13312
	ds_read_b128 v[100:103], v229 offset:13312
	v_cmp_le_u32_e32 vcc, v86, v2
	ds_read_b128 v[104:107], v230 offset:13824
	ds_read_b128 v[108:111], v231 offset:13824
	s_waitcnt vmcnt(16) lgkmcnt(6)
	v_mfma_f32_16x16x32_bf16 v[92:95], v[72:75], v[136:139], v[92:95]
	s_mov_b64 s[14:15], 0
	s_waitcnt lgkmcnt(5)
	v_mfma_f32_16x16x32_bf16 v[112:115], v[56:59], v[132:135], 0
	s_waitcnt lgkmcnt(4)
	v_mfma_f32_16x16x32_bf16 v[112:115], v[48:51], v[136:139], v[112:115]
	s_nop 2
	v_cndmask_b32_e32 v116, v217, v93, vcc
	v_cmp_le_u32_e32 vcc, v84, v2
	v_cndmask_b32_e64 v87, v217, v92, s[0:1]
	s_nop 0
	v_cndmask_b32_e32 v117, v217, v94, vcc
	v_cmp_le_u32_e32 vcc, v83, v2
	s_nop 1
	v_cndmask_b32_e32 v118, v217, v95, vcc
	s_waitcnt lgkmcnt(3)
	v_mfma_f32_16x16x32_bf16 v[92:95], v[96:99], v[132:135], 0
	v_cmp_le_u32_e32 vcc, v82, v2
	s_nop 1
	v_cndmask_b32_e32 v112, v217, v112, vcc
	v_cmp_le_u32_e32 vcc, v81, v2
	s_waitcnt lgkmcnt(2)
	v_mfma_f32_16x16x32_bf16 v[92:95], v[100:103], v[136:139], v[92:95]
	v_add_u32_e32 v101, 32, v85
	v_cndmask_b32_e32 v113, v217, v113, vcc
	v_cmp_le_u32_e32 vcc, v80, v2
	s_waitcnt lgkmcnt(1)
	v_mfma_f32_16x16x32_bf16 v[96:99], v[104:107], v[132:135], 0
	v_cndmask_b32_e32 v114, v217, v114, vcc
	v_cmp_le_u32_e32 vcc, v3, v2
	s_waitcnt lgkmcnt(0)
	v_mfma_f32_16x16x32_bf16 v[96:99], v[108:111], v[136:139], v[96:99]
	v_cndmask_b32_e32 v100, v217, v115, vcc
	v_cmp_le_u32_e32 vcc, v101, v2
	v_add_u32_e32 v101, 33, v85
	s_nop 0
	v_cndmask_b32_e32 v92, v217, v92, vcc
	v_cmp_le_u32_e32 vcc, v101, v2
	v_add_u32_e32 v101, 34, v85
	s_nop 0
	v_cndmask_b32_e32 v93, v217, v93, vcc
	v_cmp_le_u32_e32 vcc, v101, v2
	v_add_u32_e32 v101, 35, v85
	s_nop 0
	v_cndmask_b32_e32 v94, v217, v94, vcc
	v_cmp_le_u32_e32 vcc, v101, v2
	v_add_u32_e32 v101, 36, v85
	s_nop 0
	v_cndmask_b32_e32 v95, v217, v95, vcc
	v_cmp_le_u32_e32 vcc, v101, v2
	v_add_u32_e32 v101, 37, v85
	s_nop 0
	v_cndmask_b32_e32 v96, v217, v96, vcc
	v_cmp_le_u32_e32 vcc, v101, v2
	v_add_u32_e32 v101, 38, v85
	s_nop 0
	v_cndmask_b32_e32 v97, v217, v97, vcc
	v_cmp_le_u32_e32 vcc, v101, v2
	v_add_u32_e32 v101, 39, v85
	s_nop 0
	v_cndmask_b32_e32 v98, v217, v98, vcc
	v_cmp_le_u32_e32 vcc, v101, v2
	v_max3_f32 v101, v87, s62, v116
	v_max3_f32 v101, v101, v117, v118
	v_max3_f32 v101, v101, v112, v113
	v_max3_f32 v101, v101, v114, v100
	v_max3_f32 v101, v101, v92, v93
	v_max3_f32 v101, v101, v94, v95
	v_cndmask_b32_e32 v99, v217, v99, vcc
	v_max3_f32 v101, v101, v96, v97
	v_max3_f32 v101, v101, v98, v99
	ds_bpermute_b32 v102, v0, v101
	s_waitcnt lgkmcnt(0)
	v_max_f32_e32 v102, v102, v102
	v_max_f32_e32 v101, v101, v102
	ds_bpermute_b32 v102, v222, v101
	s_waitcnt lgkmcnt(0)
	v_max3_f32 v223, v226, v101, v102
	v_sub_f32_e32 v87, v87, v223
	v_exp_f32_e32 v87, v87
	v_sub_f32_e32 v102, v116, v223
	v_exp_f32_e32 v102, v102
	v_sub_f32_e32 v103, v117, v223
	v_sub_f32_e32 v92, v92, v223
	v_exp_f32_e32 v103, v103
	v_sub_f32_e32 v104, v118, v223
	v_exp_f32_e32 v130, v92
	v_sub_f32_e32 v92, v93, v223
	v_exp_f32_e32 v104, v104
	v_sub_f32_e32 v106, v112, v223
	v_exp_f32_e32 v131, v92
	v_sub_f32_e32 v92, v94, v223
	v_add_f32_e32 v105, 0, v87
	v_exp_f32_e32 v106, v106
	v_sub_f32_e32 v107, v113, v223
	v_exp_f32_e32 v140, v92
	v_sub_f32_e32 v92, v95, v223
	v_add_f32_e32 v105, v102, v105
	v_exp_f32_e32 v107, v107
	v_sub_f32_e32 v108, v114, v223
	v_exp_f32_e32 v141, v92
	v_sub_f32_e32 v92, v96, v223
	v_add_f32_e32 v105, v103, v105
	v_exp_f32_e32 v108, v108
	v_sub_f32_e32 v100, v100, v223
	v_exp_f32_e32 v142, v92
	v_sub_f32_e32 v92, v97, v223
	v_sub_f32_e32 v101, v226, v223
	v_add_f32_e32 v105, v104, v105
	v_exp_f32_e32 v100, v100
	v_exp_f32_e32 v143, v92
	v_sub_f32_e32 v92, v98, v223
	v_add_f32_e32 v105, v106, v105
	v_exp_f32_e32 v224, v92
	v_sub_f32_e32 v116, v99, v223
	v_exp_f32_e32 v128, v101
	v_cvt_pk_bf16_f32 v92, v87, v102
	v_cvt_pk_bf16_f32 v93, v103, v104
	v_cvt_pk_bf16_f32 v94, v106, v107
	v_cvt_pk_bf16_f32 v95, v108, v100
	ds_read_b64_tr_b16 v[98:99], v225 offset:576
	ds_read_b64_tr_b16 v[96:97], v225
	v_add_f32_e32 v105, v107, v105
	v_add_f32_e32 v105, v108, v105
	v_add_f32_e32 v129, v100, v105
	ds_read_b64_tr_b16 v[106:107], v225 offset:608
	ds_read_b64_tr_b16 v[104:105], v225 offset:32
	ds_read_b64_tr_b16 v[108:109], v225 offset:64
	ds_read_b64_tr_b16 v[112:113], v225 offset:96
	ds_read_b64_tr_b16 v[110:111], v225 offset:640
	ds_read_b64_tr_b16 v[114:115], v225 offset:672
	v_pk_mul_f32 v[102:103], v[170:171], v[128:129] op_sel_hi:[1,0]
	v_pk_mul_f32 v[100:101], v[168:169], v[128:129] op_sel_hi:[1,0]
	v_exp_f32_e32 v87, v116
	v_pk_mul_f32 v[118:119], v[166:167], v[128:129] op_sel_hi:[1,0]
	s_waitcnt lgkmcnt(6)
	v_mfma_f32_16x16x32_bf16 v[96:99], v[96:99], v[92:95], v[100:103]
	v_mul_f32_e64 v116, v164, v128
	v_mul_f32_e64 v117, v165, v128
	s_nop 0
	v_pk_mul_f32 v[102:103], v[158:159], v[128:129] op_sel_hi:[1,0]
	v_pk_mul_f32 v[100:101], v[156:157], v[128:129] op_sel_hi:[1,0]
	s_waitcnt lgkmcnt(4)
	s_nop 0
	v_mfma_f32_16x16x32_bf16 v[100:103], v[104:107], v[92:95], v[100:103]
	v_mul_f32_e64 v106, v162, v128
	v_mul_f32_e64 v107, v163, v128
	v_pk_mul_f32 v[104:105], v[160:161], v[128:129] op_sel_hi:[1,0]
	s_waitcnt lgkmcnt(1)
	s_nop 0
	v_mfma_f32_16x16x32_bf16 v[104:107], v[108:111], v[92:95], v[104:107]
	v_cvt_pk_bf16_f32 v108, v130, v131
	v_cvt_pk_bf16_f32 v109, v140, v141
	v_cvt_pk_bf16_f32 v110, v142, v143
	v_cvt_pk_bf16_f32 v111, v224, v87
	ds_read_b64_tr_b16 v[122:123], v225 offset:5184
	ds_read_b64_tr_b16 v[120:121], v225 offset:4608
	s_waitcnt lgkmcnt(0)
	v_mfma_f32_16x16x32_bf16 v[152:155], v[120:123], v[108:111], v[96:99]
	s_nop 2
	v_add_f32_e32 v96, v130, v129
	v_add_f32_e32 v96, v131, v96
	v_add_f32_e32 v96, v140, v96
	v_mfma_f32_16x16x32_bf16 v[92:95], v[112:115], v[92:95], v[116:119]
	ds_read_b64_tr_b16 v[114:115], v225 offset:5216
	ds_read_b64_tr_b16 v[112:113], v225 offset:4640
	s_nop 0
	ds_read_b64_tr_b16 v[116:117], v225 offset:4672
	ds_read_b64_tr_b16 v[124:125], v225 offset:4704
	ds_read_b64_tr_b16 v[118:119], v225 offset:5248
	ds_read_b64_tr_b16 v[126:127], v225 offset:5280
	v_add_f32_e32 v96, v141, v96
	v_add_f32_e32 v96, v142, v96
	v_add_f32_e32 v96, v143, v96
	s_waitcnt lgkmcnt(0)
	v_add_f32_e32 v96, v224, v96
	v_add_f32_e32 v224, v87, v96
	s_waitcnt lgkmcnt(4)
	v_mfma_f32_16x16x32_bf16 v[148:151], v[112:115], v[108:111], v[100:103]
	v_fmac_f32_e32 v224, v227, v128
	s_waitcnt lgkmcnt(1)
	v_mfma_f32_16x16x32_bf16 v[144:147], v[116:119], v[108:111], v[104:107]
	s_waitcnt lgkmcnt(0)
	v_mfma_f32_16x16x32_bf16 v[140:143], v[124:127], v[108:111], v[92:95]

.LBB0_559:
	s_setprio 1
	s_cmp_lt_i32 s78, 2
	s_cselect_b64 s[18:19], -1, 0
	s_cmp_lt_i32 s67, 2
	s_cselect_b64 s[38:39], -1, 0
	s_or_b64 s[14:15], s[18:19], s[38:39]
	s_mov_b64 s[0:1], -1
	v_readfirstlane_b32 s81, v0
	v_readfirstlane_b32 s82, v0
	v_readfirstlane_b32 s79, v0
	s_andn2_b64 vcc, exec, s[14:15]
	v_readfirstlane_b32 s80, v0
	s_cbranch_vccnz .LBB0_545
	s_cmp_eq_u32 s75, 1
	s_cselect_b32 s0, 2, 4
	s_lshr_b32 s14, s8, s0
	s_lshl_b32 s15, s76, 6
	s_lshr_b32 s1, 0x800, s0
	s_add_i32 s14, s14, s15
	s_add_i32 s1, s1, -1
	v_add_u32_e32 v124, s14, v191
	v_min_i32_e32 v2, s1, v124
	v_cmp_lt_i32_e32 vcc, -1, v124
	s_lshl_b32 s20, -1, s0
	s_andn2_b32 s20, s8, s20
	v_cndmask_b32_e32 v2, 0, v2, vcc
	v_lshlrev_b32_e32 v2, s0, v2
	v_add_u32_e32 v2, s20, v2
	v_lshl_or_b32 v2, v2, 6, v180
	v_ashrrev_i32_e32 v3, 31, v2
	v_lshlrev_b64 v[2:3], 1, v[2:3]
	s_waitcnt lgkmcnt(0)
	v_lshl_add_u64 v[48:49], s[10:11], 0, v[2:3]
	v_lshl_add_u64 v[2:3], s[12:13], 0, v[2:3]
	global_load_dwordx4 v[56:59], v[48:49], off
	s_nop 0
	global_load_dwordx4 v[48:51], v[2:3], off
	v_add_u32_e32 v2, 8, v124
	v_min_i32_e32 v3, s1, v2
	v_cmp_lt_i32_e32 vcc, -1, v2
	s_nop 1
	v_cndmask_b32_e32 v2, 0, v3, vcc
	v_lshlrev_b32_e32 v2, s0, v2
	v_add_u32_e32 v2, s20, v2
	v_lshl_or_b32 v2, v2, 6, v180
	v_ashrrev_i32_e32 v3, 31, v2
	v_lshlrev_b64 v[2:3], 1, v[2:3]
	v_lshl_add_u64 v[60:61], s[10:11], 0, v[2:3]
	v_lshl_add_u64 v[2:3], s[12:13], 0, v[2:3]
	global_load_dwordx4 v[72:75], v[60:61], off
	s_nop 0
	global_load_dwordx4 v[60:63], v[2:3], off
	v_add_u32_e32 v2, 16, v124
	v_min_i32_e32 v3, s1, v2
	v_cmp_lt_i32_e32 vcc, -1, v2
	s_nop 1
	v_cndmask_b32_e32 v2, 0, v3, vcc
	v_lshlrev_b32_e32 v2, s0, v2
	v_add_u32_e32 v2, s20, v2
	v_lshl_or_b32 v2, v2, 6, v180
	v_ashrrev_i32_e32 v3, 31, v2
	v_lshlrev_b64 v[2:3], 1, v[2:3]
	v_lshl_add_u64 v[80:81], s[10:11], 0, v[2:3]
	v_lshl_add_u64 v[2:3], s[12:13], 0, v[2:3]
	global_load_dwordx4 v[84:87], v[80:81], off
	s_nop 0
	global_load_dwordx4 v[80:83], v[2:3], off
	v_add_u32_e32 v2, 24, v124
	v_min_i32_e32 v3, s1, v2
	v_cmp_lt_i32_e32 vcc, -1, v2
	s_nop 1
	v_cndmask_b32_e32 v2, 0, v3, vcc
	v_lshlrev_b32_e32 v2, s0, v2
	v_add_u32_e32 v2, s20, v2
	v_lshl_or_b32 v2, v2, 6, v180
	v_ashrrev_i32_e32 v3, 31, v2
	v_lshlrev_b64 v[2:3], 1, v[2:3]
	v_lshl_add_u64 v[92:93], s[10:11], 0, v[2:3]
	v_lshl_add_u64 v[2:3], s[12:13], 0, v[2:3]
	global_load_dwordx4 v[96:99], v[92:93], off
	s_nop 0
	global_load_dwordx4 v[92:95], v[2:3], off
	v_add_u32_e32 v2, 32, v124
	v_min_i32_e32 v3, s1, v2
	v_cmp_lt_i32_e32 vcc, -1, v2
	s_nop 1
	v_cndmask_b32_e32 v2, 0, v3, vcc
	v_lshlrev_b32_e32 v2, s0, v2
	v_add_u32_e32 v2, s20, v2
	v_lshl_or_b32 v2, v2, 6, v180
	v_ashrrev_i32_e32 v3, 31, v2
	v_lshlrev_b64 v[2:3], 1, v[2:3]
	v_lshl_add_u64 v[100:101], s[10:11], 0, v[2:3]
	v_lshl_add_u64 v[2:3], s[12:13], 0, v[2:3]
	global_load_dwordx4 v[104:107], v[100:101], off
	s_nop 0
	global_load_dwordx4 v[100:103], v[2:3], off
	v_add_u32_e32 v2, 40, v124
	v_min_i32_e32 v3, s1, v2
	v_cmp_lt_i32_e32 vcc, -1, v2
	s_nop 1
	v_cndmask_b32_e32 v2, 0, v3, vcc
	v_lshlrev_b32_e32 v2, s0, v2
	v_add_u32_e32 v2, s20, v2
	v_lshl_or_b32 v2, v2, 6, v180
	v_ashrrev_i32_e32 v3, 31, v2
	v_lshlrev_b64 v[2:3], 1, v[2:3]
	v_lshl_add_u64 v[108:109], s[10:11], 0, v[2:3]
	v_lshl_add_u64 v[2:3], s[12:13], 0, v[2:3]
	global_load_dwordx4 v[112:115], v[108:109], off
	s_nop 0
	global_load_dwordx4 v[108:111], v[2:3], off
	v_add_u32_e32 v2, 48, v124
	v_min_i32_e32 v3, s1, v2
	v_cmp_lt_i32_e32 vcc, -1, v2
	s_nop 1
	v_cndmask_b32_e32 v2, 0, v3, vcc
	v_lshlrev_b32_e32 v2, s0, v2
	v_add_u32_e32 v2, s20, v2
	v_lshl_or_b32 v2, v2, 6, v180
	v_ashrrev_i32_e32 v3, 31, v2
	v_lshlrev_b64 v[2:3], 1, v[2:3]
	v_lshl_add_u64 v[116:117], s[10:11], 0, v[2:3]
	v_lshl_add_u64 v[2:3], s[12:13], 0, v[2:3]
	global_load_dwordx4 v[120:123], v[116:117], off
	s_nop 0
	global_load_dwordx4 v[116:119], v[2:3], off
	v_add_u32_e32 v2, 56, v124
	v_min_i32_e32 v3, s1, v2
	v_cmp_lt_i32_e32 vcc, -1, v2
	s_nop 1
	v_cndmask_b32_e32 v2, 0, v3, vcc
	v_lshlrev_b32_e32 v2, s0, v2
	v_add_u32_e32 v2, s20, v2
	v_lshl_or_b32 v2, v2, 6, v180
	v_ashrrev_i32_e32 v3, 31, v2
	v_lshlrev_b64 v[2:3], 1, v[2:3]
	v_lshl_add_u64 v[124:125], s[10:11], 0, v[2:3]
	v_lshl_add_u64 v[2:3], s[12:13], 0, v[2:3]
	global_load_dwordx4 v[128:131], v[124:125], off
	s_nop 0
	global_load_dwordx4 v[124:127], v[2:3], off
	s_andn2_b64 vcc, exec, s[16:17]
	s_mov_b64 s[0:1], 0
	s_cbranch_vccnz .LBB0_564
	s_add_i32 s16, s76, 1
	s_cmp_lt_i32 s76, 2
	s_mov_b64 s[14:15], -1
	s_cbranch_scc1 .LBB0_563
	s_add_i32 s17, s75, 1
	s_cmp_lt_i32 s75, 2
	s_cselect_b64 s[14:15], -1, 0
	s_and_b64 s[20:21], s[14:15], exec
	s_cselect_b32 s16, s66, s16
	s_mov_b32 s75, s17

.LBB0_566:
	s_setprio 0
	s_waitcnt vmcnt(0)
	s_barrier
	s_and_saveexec_b64 s[0:1], s[92:93]
	s_cbranch_execz .LBB0_618
	s_add_i32 s4, 0, 0x23fc0
	s_waitcnt vmcnt(3)
	v_mov_b32_e32 v0, s4
	s_waitcnt vmcnt(0) expcnt(0) lgkmcnt(0)
	ds_read_b32 v2, v0
	s_add_i32 s4, 0, 0x23fc4
	v_mov_b32_e32 v0, s4
	ds_read_b32 v0, v0
	s_waitcnt lgkmcnt(1)
	v_cmp_ne_u32_e32 vcc, 0, v2
	s_cbranch_vccnz .LBB0_582
	v_readlane_b32 s4, v254, 0
	s_mul_i32 s18, s35, s4
	s_add_u32 s4, s30, 0x1000
	s_addc_u32 s5, s31, 0
	s_add_u32 s6, s30, 0x1100
	s_addc_u32 s7, s31, 0
	s_add_u32 s8, s30, 0x1200
	s_addc_u32 s9, s31, 0
	s_add_u32 s10, s30, 0x1300
	s_mul_i32 s18, s18, s34
	s_addc_u32 s11, s31, 0
	s_mov_b32 s19, 1
	v_mov_b32_e32 v16, 0
	s_branch .LBB0_570
